# NSA sel/window: exp and P.V MFMAs interleaved in four 16-key phases, same summation order (plus v24 changes)
# baseline (speedup 1.0000x reference)
; DI unsigned pk2(float lo, float hi) { f32x2 v = {lo, hi}; return __builtin_bit_cast(unsigned, __builtin_convertvector(v, bf2_t)); }
; DI float fast_exp2(float x) { return __builtin_amdgcn_exp2f(x); }
; #define MFMA32(a, b, c) __builtin_amdgcn_mfma_f32_32x32x16_bf16((a), (b), (c), 0, 0, 0)
; DI void pv_frag(const VFrag& V, const f32x16& p, f32x16& o0, f32x16& o1) {
; #pragma unroll
;     for (int s = 0; s < 2; ++s) {
;         u32x4 pw; pw.x = pk2(p[8 * s], p[8 * s + 1]); pw.y = pk2(p[8 * s + 2], p[8 * s + 3]); pw.z = pk2(p[8 * s + 4], p[8 * s + 5]); pw.w = pk2(p[8 * s + 6], p[8 * s + 7]);
;         const bf16x8 pf = __builtin_bit_cast(bf16x8, pw);
; #pragma unroll
;         for (int d0 = 0; d0 < 2; ++d0) {
;             const u32x2 lo = V.v[(2 * s + d0) * 2], h2 = V.v[(2 * s + d0) * 2 + 1];
;             u32x4 vw; vw.x = lo.x; vw.y = lo.y; vw.z = h2.x; vw.w = h2.y;
;             const bf16x8 vf = __builtin_bit_cast(bf16x8, vw);
;             if (d0 == 0) o0 = MFMA32(vf, pf, o0); else o1 = MFMA32(vf, pf, o1);
;         }
;     }
; }
; DI float soft_update(Soft& f, f32x16& x0, f32x16& x1, bool hasO) {
;     ...
;     float ls = 0.f;
; #pragma unroll
;     for (int r = 0; r < 16; ++r) { x0[r] = fast_exp2(x0[r]); x1[r] = fast_exp2(x1[r]); ls += x0[r] + x1[r]; }
;     f.l += ls;
.LBB0_1007:
	s_or_b64 s[4:5], s[4:5], s[6:7]
	v_exp_f32_e32 v96, v96
	v_exp_f32_e32 v97, v97
	v_exp_f32_e32 v98, v98
	v_exp_f32_e32 v99, v99
	v_exp_f32_e32 v100, v100
	v_exp_f32_e32 v101, v101
	v_exp_f32_e32 v102, v102
	v_exp_f32_e32 v103, v103
	v_exp_f32_e32 v104, v104
	v_cvt_pk_bf16_f32 v178, v96, v97
	v_cvt_pk_bf16_f32 v179, v98, v99
	v_cvt_pk_bf16_f32 v180, v100, v101
	v_cvt_pk_bf16_f32 v181, v102, v103
	v_exp_f32_e32 v105, v105
	s_waitcnt lgkmcnt(14)
	v_mfma_f32_32x32x16_bf16 v[64:79], v[140:143], v[178:181], v[64:79]
	v_exp_f32_e32 v106, v106
	s_waitcnt lgkmcnt(10)
	v_mfma_f32_32x32x16_bf16 v[48:63], v[136:139], v[178:181], v[48:63]
	v_exp_f32_e32 v107, v107
	v_exp_f32_e32 v108, v108
	v_exp_f32_e32 v109, v109
	v_exp_f32_e32 v110, v110
	v_exp_f32_e32 v111, v111
	v_exp_f32_e32 v80, v80
	v_cvt_pk_bf16_f32 v182, v104, v105
	v_cvt_pk_bf16_f32 v183, v106, v107
	v_cvt_pk_bf16_f32 v184, v108, v109
	v_cvt_pk_bf16_f32 v185, v110, v111
	v_exp_f32_e32 v81, v81
	v_exp_f32_e32 v82, v82
	v_mfma_f32_32x32x16_bf16 v[64:79], v[132:135], v[182:185], v[64:79]
	v_exp_f32_e32 v83, v83
	s_waitcnt lgkmcnt(8)
	v_mfma_f32_32x32x16_bf16 v[48:63], v[128:131], v[182:185], v[48:63]
	v_exp_f32_e32 v84, v84
	v_exp_f32_e32 v85, v85
	v_exp_f32_e32 v86, v86
	v_exp_f32_e32 v87, v87
	v_exp_f32_e32 v88, v88
	v_cvt_pk_bf16_f32 v178, v80, v81
	v_cvt_pk_bf16_f32 v179, v82, v83
	v_cvt_pk_bf16_f32 v180, v84, v85
	v_cvt_pk_bf16_f32 v181, v86, v87
	v_exp_f32_e32 v89, v89
	v_exp_f32_e32 v90, v90
	s_waitcnt lgkmcnt(6)
	v_mfma_f32_32x32x16_bf16 v[64:79], v[124:127], v[178:181], v[64:79]
	v_exp_f32_e32 v91, v91
	s_waitcnt lgkmcnt(4)
	v_mfma_f32_32x32x16_bf16 v[48:63], v[10:13], v[178:181], v[48:63]
	v_exp_f32_e32 v92, v92
	v_exp_f32_e32 v93, v93
	v_exp_f32_e32 v94, v94
	v_exp_f32_e32 v95, v95
	v_add_f32_e32 v248, v80, v96
	v_cvt_pk_bf16_f32 v182, v88, v89
	v_cvt_pk_bf16_f32 v183, v90, v91
	v_cvt_pk_bf16_f32 v184, v92, v93
	v_cvt_pk_bf16_f32 v185, v94, v95
	v_add_f32_e32 v249, v81, v97
	v_add_f32_e32 v248, v249, v248
	s_waitcnt lgkmcnt(2)
	v_mfma_f32_32x32x16_bf16 v[64:79], v[6:9], v[182:185], v[64:79]
	v_add_f32_e32 v249, v82, v98
	v_add_f32_e32 v249, v249, v248
	v_add_f32_e32 v248, v83, v99
	v_add_f32_e32 v248, v248, v249
	s_waitcnt lgkmcnt(0)
	v_mfma_f32_32x32x16_bf16 v[48:63], v[2:5], v[182:185], v[48:63]
	v_add_f32_e32 v249, v84, v100
	v_add_f32_e32 v249, v249, v248
	v_add_f32_e32 v248, v85, v101
	v_add_f32_e32 v248, v248, v249
	v_add_f32_e32 v249, v86, v102
	v_add_f32_e32 v249, v249, v248
	v_add_f32_e32 v248, v87, v103
	v_add_f32_e32 v248, v248, v249
	v_add_f32_e32 v249, v88, v104
	v_add_f32_e32 v249, v249, v248
	v_add_f32_e32 v248, v89, v105
	v_add_f32_e32 v248, v248, v249
	v_add_f32_e32 v249, v90, v106
	v_add_f32_e32 v249, v249, v248
	v_add_f32_e32 v248, v91, v107
	v_add_f32_e32 v248, v248, v249
	v_add_f32_e32 v249, v92, v108
	v_add_f32_e32 v249, v249, v248
	v_add_f32_e32 v248, v93, v109
	v_add_f32_e32 v248, v248, v249
	v_add_f32_e32 v249, v94, v110
	v_add_f32_e32 v249, v249, v248
	v_add_f32_e32 v248, v95, v111
	v_add_f32_e32 v248, v248, v249
	v_add_f32_e32 v211, v211, v248

; DI unsigned pk2(float lo, float hi) { f32x2 v = {lo, hi}; return __builtin_bit_cast(unsigned, __builtin_convertvector(v, bf2_t)); }
; DI float fast_exp2(float x) { return __builtin_amdgcn_exp2f(x); }
; #define MFMA32(a, b, c) __builtin_amdgcn_mfma_f32_32x32x16_bf16((a), (b), (c), 0, 0, 0)
; DI void pv_frag(const VFrag& V, const f32x16& p, f32x16& o0, f32x16& o1) {
; #pragma unroll
;     for (int s = 0; s < 2; ++s) {
;         u32x4 pw; pw.x = pk2(p[8 * s], p[8 * s + 1]); pw.y = pk2(p[8 * s + 2], p[8 * s + 3]); pw.z = pk2(p[8 * s + 4], p[8 * s + 5]); pw.w = pk2(p[8 * s + 6], p[8 * s + 7]);
;         const bf16x8 pf = __builtin_bit_cast(bf16x8, pw);
; #pragma unroll
;         for (int d0 = 0; d0 < 2; ++d0) {
;             const u32x2 lo = V.v[(2 * s + d0) * 2], h2 = V.v[(2 * s + d0) * 2 + 1];
;             u32x4 vw; vw.x = lo.x; vw.y = lo.y; vw.z = h2.x; vw.w = h2.y;
;             const bf16x8 vf = __builtin_bit_cast(bf16x8, vw);
;             if (d0 == 0) o0 = MFMA32(vf, pf, o0); else o1 = MFMA32(vf, pf, o1);
;         }
;     }
; }
; DI float soft_update(Soft& f, f32x16& x0, f32x16& x1, bool hasO) {
;     ...
;     float ls = 0.f;
; #pragma unroll
;     for (int r = 0; r < 16; ++r) { x0[r] = fast_exp2(x0[r]); x1[r] = fast_exp2(x1[r]); ls += x0[r] + x1[r]; }
;     f.l += ls;
.LBB0_1030:
	s_or_b64 s[4:5], s[4:5], s[6:7]
	v_exp_f32_e32 v128, v128
	v_exp_f32_e32 v129, v129
	v_exp_f32_e32 v130, v130
	v_exp_f32_e32 v131, v131
	v_exp_f32_e32 v132, v132
	v_exp_f32_e32 v133, v133
	v_exp_f32_e32 v134, v134
	v_exp_f32_e32 v135, v135
	v_exp_f32_e32 v136, v136
	v_cvt_pk_bf16_f32 v250, v128, v129
	v_cvt_pk_bf16_f32 v251, v130, v131
	v_cvt_pk_bf16_f32 v252, v132, v133
	v_cvt_pk_bf16_f32 v253, v134, v135
	v_exp_f32_e32 v137, v137
	s_waitcnt lgkmcnt(14)
	v_mfma_f32_32x32x16_bf16 v[96:111], v[184:187], v[250:253], v[96:111]
	v_exp_f32_e32 v138, v138
	s_waitcnt lgkmcnt(10)
	v_mfma_f32_32x32x16_bf16 v[80:95], v[180:183], v[250:253], v[80:95]
	v_exp_f32_e32 v139, v139
	v_exp_f32_e32 v140, v140
	v_exp_f32_e32 v141, v141
	v_exp_f32_e32 v142, v142
	v_exp_f32_e32 v143, v143
	v_exp_f32_e32 v112, v112
	v_cvt_pk_bf16_f32 v250, v136, v137
	v_cvt_pk_bf16_f32 v251, v138, v139
	v_cvt_pk_bf16_f32 v252, v140, v141
	v_cvt_pk_bf16_f32 v253, v142, v143
	v_exp_f32_e32 v113, v113
	v_exp_f32_e32 v114, v114
	v_mfma_f32_32x32x16_bf16 v[96:111], v[176:179], v[250:253], v[96:111]
	v_exp_f32_e32 v115, v115
	s_waitcnt lgkmcnt(8)
	v_mfma_f32_32x32x16_bf16 v[80:95], v[172:175], v[250:253], v[80:95]
	v_exp_f32_e32 v116, v116
	v_exp_f32_e32 v117, v117
	v_exp_f32_e32 v118, v118
	v_exp_f32_e32 v119, v119
	v_exp_f32_e32 v120, v120
	v_cvt_pk_bf16_f32 v250, v112, v113
	v_cvt_pk_bf16_f32 v251, v114, v115
	v_cvt_pk_bf16_f32 v252, v116, v117
	v_cvt_pk_bf16_f32 v253, v118, v119
	v_exp_f32_e32 v121, v121
	v_exp_f32_e32 v122, v122
	s_waitcnt lgkmcnt(6)
	v_mfma_f32_32x32x16_bf16 v[96:111], v[168:171], v[250:253], v[96:111]
	v_exp_f32_e32 v123, v123
	s_waitcnt lgkmcnt(4)
	v_mfma_f32_32x32x16_bf16 v[80:95], v[10:13], v[250:253], v[80:95]
	v_exp_f32_e32 v124, v124
	v_exp_f32_e32 v125, v125
	v_exp_f32_e32 v126, v126
	v_exp_f32_e32 v127, v127
	v_add_f32_e32 v14, v112, v128
	v_cvt_pk_bf16_f32 v250, v120, v121
	v_cvt_pk_bf16_f32 v251, v122, v123
	v_cvt_pk_bf16_f32 v252, v124, v125
	v_cvt_pk_bf16_f32 v253, v126, v127
	v_add_f32_e32 v15, v113, v129
	v_add_f32_e32 v14, v15, v14
	s_waitcnt lgkmcnt(2)
	v_mfma_f32_32x32x16_bf16 v[96:111], v[6:9], v[250:253], v[96:111]
	v_add_f32_e32 v15, v114, v130
	v_add_f32_e32 v15, v15, v14
	v_add_f32_e32 v14, v115, v131
	v_add_f32_e32 v14, v14, v15
	s_waitcnt lgkmcnt(0)
	v_mfma_f32_32x32x16_bf16 v[80:95], v[2:5], v[250:253], v[80:95]
	v_add_f32_e32 v15, v116, v132
	v_add_f32_e32 v15, v15, v14
	v_add_f32_e32 v14, v117, v133
	v_add_f32_e32 v14, v14, v15
	v_add_f32_e32 v15, v118, v134
	v_add_f32_e32 v15, v15, v14
	v_add_f32_e32 v14, v119, v135
	v_add_f32_e32 v14, v14, v15
	v_add_f32_e32 v15, v120, v136
	v_add_f32_e32 v15, v15, v14
	v_add_f32_e32 v14, v121, v137
	v_add_f32_e32 v14, v14, v15
	v_add_f32_e32 v15, v122, v138
	v_add_f32_e32 v15, v15, v14
	v_add_f32_e32 v14, v123, v139
	v_add_f32_e32 v14, v14, v15
	v_add_f32_e32 v15, v124, v140
	v_add_f32_e32 v15, v15, v14
	v_add_f32_e32 v14, v125, v141
	v_add_f32_e32 v14, v14, v15
	v_add_f32_e32 v15, v126, v142
	v_add_f32_e32 v15, v15, v14
	v_add_f32_e32 v14, v127, v143
	v_add_f32_e32 v14, v14, v15
	v_add_f32_e32 v210, v210, v14
	s_andn2_b64 vcc, exec, s[76:77]
	s_xor_b32 s1, s1, 1
	s_cbranch_vccnz .LBB0_1015
